# a0early P12: K-loop A0 fragment reads moved one load segment earlier (12,4,8,0 -> 8,4,8,4 balance) with counted vmcnt(10)
# baseline (speedup 1.0000x reference)
.LBB0_1270:
	s_ashr_i32 s23, s22, 31
	v_cmp_lt_i64_e32 vcc, s[0:1], v[140:141]
	s_lshl_b64 s[0:1], s[22:23], 20
	s_add_u32 s24, s6, s0
	s_addc_u32 s25, s7, s1
	s_and_b64 s[0:1], vcc, exec
	s_cselect_b32 s23, s25, s35
	s_cselect_b32 s56, s24, s34
	s_ashr_i32 s21, s20, 31
	s_lshl_b64 s[0:1], s[20:21], 20
	s_add_u32 s26, s36, s0
	s_addc_u32 s27, s37, s1
	s_and_b64 s[0:1], vcc, exec
	s_cselect_b32 s21, s27, s31
	s_cselect_b32 s57, s26, s30
	s_add_u32 s0, s34, 0x80080
	s_addc_u32 s1, s35, 0
	s_add_u32 s58, s30, 0x100
	v_mov_b32_e32 v0, 0
	s_addc_u32 s59, s31, 0
	s_mov_b32 s60, -2
	v_mov_b32_e32 v1, v0
	v_mov_b32_e32 v2, v0
	v_mov_b32_e32 v3, v0
	v_mov_b32_e32 v4, v0
	v_mov_b32_e32 v5, v0
	v_mov_b32_e32 v6, v0
	v_mov_b32_e32 v7, v0
	v_mov_b32_e32 v16, v0
	v_mov_b32_e32 v17, v0
	v_mov_b32_e32 v18, v0
	v_mov_b32_e32 v19, v0
	v_mov_b32_e32 v20, v0
	v_mov_b32_e32 v21, v0
	v_mov_b32_e32 v22, v0
	v_mov_b32_e32 v23, v0
	v_mov_b32_e32 v32, v0
	v_mov_b32_e32 v33, v0
	v_mov_b32_e32 v34, v0
	v_mov_b32_e32 v35, v0
	v_mov_b32_e32 v36, v0
	v_mov_b32_e32 v37, v0
	v_mov_b32_e32 v38, v0
	v_mov_b32_e32 v39, v0
	v_mov_b32_e32 v48, v0
	v_mov_b32_e32 v49, v0
	v_mov_b32_e32 v50, v0
	v_mov_b32_e32 v51, v0
	v_mov_b32_e32 v52, v0
	v_mov_b32_e32 v53, v0
	v_mov_b32_e32 v54, v0
	v_mov_b32_e32 v55, v0
	v_mov_b32_e32 v8, v0
	v_mov_b32_e32 v9, v0
	v_mov_b32_e32 v10, v0
	v_mov_b32_e32 v11, v0
	v_mov_b32_e32 v12, v0
	v_mov_b32_e32 v13, v0
	v_mov_b32_e32 v14, v0
	v_mov_b32_e32 v15, v0
	v_mov_b32_e32 v24, v0
	v_mov_b32_e32 v25, v0
	v_mov_b32_e32 v26, v0
	v_mov_b32_e32 v27, v0
	v_mov_b32_e32 v28, v0
	v_mov_b32_e32 v29, v0
	v_mov_b32_e32 v30, v0
	v_mov_b32_e32 v31, v0
	v_mov_b32_e32 v40, v0
	v_mov_b32_e32 v41, v0
	v_mov_b32_e32 v42, v0
	v_mov_b32_e32 v43, v0
	v_mov_b32_e32 v44, v0
	v_mov_b32_e32 v45, v0
	v_mov_b32_e32 v46, v0
	v_mov_b32_e32 v47, v0
	v_mov_b32_e32 v56, v0
	v_mov_b32_e32 v57, v0
	v_mov_b32_e32 v58, v0
	v_mov_b32_e32 v59, v0
	v_mov_b32_e32 v60, v0
	v_mov_b32_e32 v61, v0
	v_mov_b32_e32 v62, v0
	v_mov_b32_e32 v63, v0
	v_mov_b32_e32 v64, v0
	v_mov_b32_e32 v65, v0
	v_mov_b32_e32 v66, v0
	v_mov_b32_e32 v67, v0
	v_mov_b32_e32 v68, v0
	v_mov_b32_e32 v69, v0
	v_mov_b32_e32 v70, v0
	v_mov_b32_e32 v71, v0
	v_mov_b32_e32 v80, v0
	v_mov_b32_e32 v81, v0
	v_mov_b32_e32 v82, v0
	v_mov_b32_e32 v83, v0
	v_mov_b32_e32 v84, v0
	v_mov_b32_e32 v85, v0
	v_mov_b32_e32 v86, v0
	v_mov_b32_e32 v87, v0
	v_mov_b32_e32 v96, v0
	v_mov_b32_e32 v97, v0
	v_mov_b32_e32 v98, v0
	v_mov_b32_e32 v99, v0
	v_mov_b32_e32 v100, v0
	v_mov_b32_e32 v101, v0
	v_mov_b32_e32 v102, v0
	v_mov_b32_e32 v103, v0
	v_mov_b32_e32 v112, v0
	v_mov_b32_e32 v113, v0
	v_mov_b32_e32 v114, v0
	v_mov_b32_e32 v115, v0
	v_mov_b32_e32 v116, v0
	v_mov_b32_e32 v117, v0
	v_mov_b32_e32 v118, v0
	v_mov_b32_e32 v119, v0
	v_mov_b32_e32 v72, v0
	v_mov_b32_e32 v73, v0
	v_mov_b32_e32 v74, v0
	v_mov_b32_e32 v75, v0
	v_mov_b32_e32 v76, v0
	v_mov_b32_e32 v77, v0
	v_mov_b32_e32 v78, v0
	v_mov_b32_e32 v79, v0
	v_mov_b32_e32 v88, v0
	v_mov_b32_e32 v89, v0
	v_mov_b32_e32 v90, v0
	v_mov_b32_e32 v91, v0
	v_mov_b32_e32 v92, v0
	v_mov_b32_e32 v93, v0
	v_mov_b32_e32 v94, v0
	v_mov_b32_e32 v95, v0
	v_mov_b32_e32 v104, v0
	v_mov_b32_e32 v105, v0
	v_mov_b32_e32 v106, v0
	v_mov_b32_e32 v107, v0
	v_mov_b32_e32 v108, v0
	v_mov_b32_e32 v109, v0
	v_mov_b32_e32 v110, v0
	v_mov_b32_e32 v111, v0
	v_mov_b32_e32 v120, v0
	v_mov_b32_e32 v121, v0
	v_mov_b32_e32 v122, v0
	v_mov_b32_e32 v123, v0
	v_mov_b32_e32 v124, v0
	v_mov_b32_e32 v125, v0
	v_mov_b32_e32 v126, v0
	v_mov_b32_e32 v127, v0
	ds_read_b128 v[144:147], v155
	ds_read_b128 v[148:151], v155 offset:1024
	ds_read_b128 v[160:163], v155 offset:2048
	ds_read_b128 v[164:167], v155 offset:3072
	v_lshl_add_u32 v252, s28, 8, v152
	v_ashrrev_i32_e32 v253, 31, v252
	v_lshl_add_u64 v[254:255], v[252:253], 2, s[8:9]
	global_load_dword v236, v[254:255], off
	global_load_dword v237, v[254:255], off offset:64
	global_load_dword v238, v[254:255], off offset:128
	global_load_dword v239, v[254:255], off offset:192
	global_load_dword v240, v[254:255], off offset:512
	global_load_dword v241, v[254:255], off offset:576
	global_load_dword v242, v[254:255], off offset:640
	global_load_dword v243, v[254:255], off offset:704
.LBB0_1271:
	s_add_u32 s30, s0, 0xfff80080
	s_addc_u32 s31, s1, -1
	s_cmp_eq_u32 s60, 28
	s_cselect_b32 s35, s23, s31
	s_cselect_b32 s34, s56, s30
	s_cselect_b32 s31, s21, s59
	s_cselect_b32 s30, s57, s58
	v_lshl_add_u64 v[168:169], s[0:1], 0, v[136:137]
	s_add_i32 m0, s29, 0xc000
	ds_read_b128 v[172:175], v156
	ds_read_b128 v[176:179], v156 offset:1024
	ds_read_b128 v[180:183], v156 offset:2048
	ds_read_b128 v[184:187], v156 offset:3072
	ds_read_b128 v[188:191], v156 offset:4096
	ds_read_b128 v[192:195], v156 offset:5120
	ds_read_b128 v[196:199], v156 offset:6144
	ds_read_b128 v[200:203], v156 offset:7168
	global_load_lds_dwordx4 v[168:169], off
	v_lshl_add_u64 v[168:169], s[0:1], 0, v[138:139]
	s_add_i32 m0, s29, 0xe000
	s_nop 0
	global_load_lds_dwordx4 v[168:169], off
	s_waitcnt lgkmcnt(8)
	s_barrier
	s_waitcnt lgkmcnt(0)
	s_setprio 1
	s_waitcnt lgkmcnt(0)
	v_mfma_f32_16x16x32_bf16 v[124:127], v[144:147], v[172:175], v[124:127]
	v_mfma_f32_16x16x32_bf16 v[120:123], v[160:163], v[172:175], v[120:123]
	v_mfma_f32_16x16x32_bf16 v[108:111], v[144:147], v[180:183], v[108:111]
	v_mfma_f32_16x16x32_bf16 v[104:107], v[160:163], v[180:183], v[104:107]
	v_mfma_f32_16x16x32_bf16 v[92:95], v[144:147], v[188:191], v[92:95]
	v_mfma_f32_16x16x32_bf16 v[88:91], v[160:163], v[188:191], v[88:91]
	v_mfma_f32_16x16x32_bf16 v[76:79], v[144:147], v[196:199], v[76:79]
	v_mfma_f32_16x16x32_bf16 v[72:75], v[160:163], v[196:199], v[72:75]
	v_mfma_f32_16x16x32_bf16 v[124:127], v[148:151], v[176:179], v[124:127]
	v_mfma_f32_16x16x32_bf16 v[120:123], v[164:167], v[176:179], v[120:123]
	v_mfma_f32_16x16x32_bf16 v[108:111], v[148:151], v[184:187], v[108:111]
	v_mfma_f32_16x16x32_bf16 v[104:107], v[164:167], v[184:187], v[104:107]
	v_mfma_f32_16x16x32_bf16 v[92:95], v[148:151], v[192:195], v[92:95]
	v_mfma_f32_16x16x32_bf16 v[88:91], v[164:167], v[192:195], v[88:91]
	v_mfma_f32_16x16x32_bf16 v[76:79], v[148:151], v[200:203], v[76:79]
	v_mfma_f32_16x16x32_bf16 v[72:75], v[164:167], v[200:203], v[72:75]
	s_setprio 0
	s_barrier
	s_add_i32 s61, s48, s38
	v_lshl_add_u64 v[168:169], s[30:31], 0, v[130:131]
	s_mov_b32 m0, s61
	ds_read_b128 v[204:207], v157
	ds_read_b128 v[208:211], v157 offset:1024
	ds_read_b128 v[212:215], v157 offset:2048
	ds_read_b128 v[216:219], v157 offset:3072
	global_load_lds_dwordx4 v[168:169], off
	v_lshl_add_u64 v[220:221], s[30:31], 0, v[134:135]
	s_add_i32 m0, s61, 0x2000
	s_nop 0
	global_load_lds_dwordx4 v[220:221], off
	s_barrier
	s_waitcnt lgkmcnt(0)
	s_setprio 1
	s_waitcnt lgkmcnt(0)
	v_mfma_f32_16x16x32_bf16 v[116:119], v[204:207], v[172:175], v[116:119]
	v_mfma_f32_16x16x32_bf16 v[112:115], v[212:215], v[172:175], v[112:115]
	v_mfma_f32_16x16x32_bf16 v[100:103], v[204:207], v[180:183], v[100:103]
	v_mfma_f32_16x16x32_bf16 v[96:99], v[212:215], v[180:183], v[96:99]
	v_mfma_f32_16x16x32_bf16 v[84:87], v[204:207], v[188:191], v[84:87]
	v_mfma_f32_16x16x32_bf16 v[80:83], v[212:215], v[188:191], v[80:83]
	v_mfma_f32_16x16x32_bf16 v[68:71], v[204:207], v[196:199], v[68:71]
	v_mfma_f32_16x16x32_bf16 v[64:67], v[212:215], v[196:199], v[64:67]
	v_mfma_f32_16x16x32_bf16 v[116:119], v[208:211], v[176:179], v[116:119]
	v_mfma_f32_16x16x32_bf16 v[112:115], v[216:219], v[176:179], v[112:115]
	v_mfma_f32_16x16x32_bf16 v[100:103], v[208:211], v[184:187], v[100:103]
	v_mfma_f32_16x16x32_bf16 v[96:99], v[216:219], v[184:187], v[96:99]
	v_mfma_f32_16x16x32_bf16 v[84:87], v[208:211], v[192:195], v[84:87]
	v_mfma_f32_16x16x32_bf16 v[80:83], v[216:219], v[192:195], v[80:83]
	v_mfma_f32_16x16x32_bf16 v[68:71], v[208:211], v[200:203], v[68:71]
	v_mfma_f32_16x16x32_bf16 v[64:67], v[216:219], v[200:203], v[64:67]
	s_setprio 0
	s_mov_b32 m0, s29
	v_lshl_add_u64 v[222:223], s[34:35], 0, v[128:129]
	s_barrier
	ds_read_b128 v[172:175], v156 offset:16384
	ds_read_b128 v[176:179], v156 offset:17408
	ds_read_b128 v[180:183], v156 offset:18432
	ds_read_b128 v[184:187], v156 offset:19456
	ds_read_b128 v[188:191], v156 offset:20480
	ds_read_b128 v[192:195], v156 offset:21504
	ds_read_b128 v[196:199], v156 offset:22528
	ds_read_b128 v[200:203], v156 offset:23552
	global_load_lds_dwordx4 v[222:223], off
	v_lshl_add_u64 v[224:225], s[34:35], 0, v[132:133]
	s_mov_b32 m0, s40
	s_nop 0
	global_load_lds_dwordx4 v[224:225], off
	s_waitcnt vmcnt(10)
	s_barrier
	s_waitcnt lgkmcnt(0)
	s_setprio 1
	s_waitcnt lgkmcnt(0)
	v_mfma_f32_16x16x32_bf16 v[60:63], v[144:147], v[172:175], v[60:63]
	v_mfma_f32_16x16x32_bf16 v[56:59], v[160:163], v[172:175], v[56:59]
	v_mfma_f32_16x16x32_bf16 v[44:47], v[144:147], v[180:183], v[44:47]
	v_mfma_f32_16x16x32_bf16 v[40:43], v[160:163], v[180:183], v[40:43]
	v_mfma_f32_16x16x32_bf16 v[28:31], v[144:147], v[188:191], v[28:31]
	v_mfma_f32_16x16x32_bf16 v[24:27], v[160:163], v[188:191], v[24:27]
	v_mfma_f32_16x16x32_bf16 v[12:15], v[144:147], v[196:199], v[12:15]
	v_mfma_f32_16x16x32_bf16 v[8:11], v[160:163], v[196:199], v[8:11]
	v_mfma_f32_16x16x32_bf16 v[60:63], v[148:151], v[176:179], v[60:63]
	v_mfma_f32_16x16x32_bf16 v[56:59], v[164:167], v[176:179], v[56:59]
	v_mfma_f32_16x16x32_bf16 v[44:47], v[148:151], v[184:187], v[44:47]
	v_mfma_f32_16x16x32_bf16 v[40:43], v[164:167], v[184:187], v[40:43]
	v_mfma_f32_16x16x32_bf16 v[28:31], v[148:151], v[192:195], v[28:31]
	v_mfma_f32_16x16x32_bf16 v[24:27], v[164:167], v[192:195], v[24:27]
	v_mfma_f32_16x16x32_bf16 v[12:15], v[148:151], v[200:203], v[12:15]
	v_mfma_f32_16x16x32_bf16 v[8:11], v[164:167], v[200:203], v[8:11]
	s_setprio 0
	s_barrier
	s_add_u32 s62, s30, 0x80000
	s_addc_u32 s63, s31, 0
	s_add_i32 s61, s49, s38
	v_lshl_add_u64 v[252:253], s[62:63], 0, v[130:131]
	s_mov_b32 m0, s61
	s_nop 0
	global_load_lds_dwordx4 v[252:253], off
	v_lshl_add_u64 v[252:253], s[62:63], 0, v[134:135]
	s_add_i32 m0, s61, 0x2000
	s_nop 0
	global_load_lds_dwordx4 v[252:253], off
	v_add_u32_e32 v159, 0x18000, v153
	ds_read_b128 v[144:147], v159
	ds_read_b128 v[148:151], v159 offset:1024
	ds_read_b128 v[160:163], v159 offset:2048
	ds_read_b128 v[164:167], v159 offset:3072
	s_waitcnt vmcnt(6)
	s_barrier
	s_setprio 1
	v_mfma_f32_16x16x32_bf16 v[52:55], v[204:207], v[172:175], v[52:55]
	v_mfma_f32_16x16x32_bf16 v[48:51], v[212:215], v[172:175], v[48:51]
	v_mfma_f32_16x16x32_bf16 v[36:39], v[204:207], v[180:183], v[36:39]
	v_mfma_f32_16x16x32_bf16 v[32:35], v[212:215], v[180:183], v[32:35]
	v_mfma_f32_16x16x32_bf16 v[20:23], v[204:207], v[188:191], v[20:23]
	v_mfma_f32_16x16x32_bf16 v[16:19], v[212:215], v[188:191], v[16:19]
	v_mfma_f32_16x16x32_bf16 v[4:7], v[204:207], v[196:199], v[4:7]
	v_mfma_f32_16x16x32_bf16 v[0:3], v[212:215], v[196:199], v[0:3]
	v_mfma_f32_16x16x32_bf16 v[52:55], v[208:211], v[176:179], v[52:55]
	v_mfma_f32_16x16x32_bf16 v[48:51], v[216:219], v[176:179], v[48:51]
	v_mfma_f32_16x16x32_bf16 v[36:39], v[208:211], v[184:187], v[36:39]
	v_mfma_f32_16x16x32_bf16 v[32:35], v[216:219], v[184:187], v[32:35]
	v_mfma_f32_16x16x32_bf16 v[20:23], v[208:211], v[192:195], v[20:23]
	v_mfma_f32_16x16x32_bf16 v[16:19], v[216:219], v[192:195], v[16:19]
	v_mfma_f32_16x16x32_bf16 v[4:7], v[208:211], v[200:203], v[4:7]
	v_mfma_f32_16x16x32_bf16 v[0:3], v[216:219], v[200:203], v[0:3]
	s_setprio 0
	s_add_i32 s61, 0, 0x18000
	s_barrier
	s_add_u32 s34, s34, 0x80000
	s_addc_u32 s35, s35, 0
	s_mov_b32 m0, s41
	v_lshl_add_u64 v[204:205], s[34:35], 0, v[128:129]
	ds_read_b128 v[172:175], v156 offset:32768
	ds_read_b128 v[176:179], v156 offset:33792
	ds_read_b128 v[180:183], v156 offset:34816
	ds_read_b128 v[184:187], v156 offset:35840
	ds_read_b128 v[188:191], v156 offset:36864
	ds_read_b128 v[192:195], v156 offset:37888
	ds_read_b128 v[196:199], v156 offset:38912
	ds_read_b128 v[200:203], v156 offset:39936
	global_load_lds_dwordx4 v[204:205], off
	v_lshl_add_u64 v[204:205], s[34:35], 0, v[132:133]
	s_mov_b32 m0, s42
	s_nop 0
	global_load_lds_dwordx4 v[204:205], off
	s_waitcnt lgkmcnt(8)
	s_barrier
	s_waitcnt lgkmcnt(0)
	s_setprio 1
	s_waitcnt lgkmcnt(0)
	v_mfma_f32_16x16x32_bf16 v[124:127], v[144:147], v[172:175], v[124:127]
	v_mfma_f32_16x16x32_bf16 v[120:123], v[160:163], v[172:175], v[120:123]
	v_mfma_f32_16x16x32_bf16 v[108:111], v[144:147], v[180:183], v[108:111]
	v_mfma_f32_16x16x32_bf16 v[104:107], v[160:163], v[180:183], v[104:107]
	v_mfma_f32_16x16x32_bf16 v[92:95], v[144:147], v[188:191], v[92:95]
	v_mfma_f32_16x16x32_bf16 v[88:91], v[160:163], v[188:191], v[88:91]
	v_mfma_f32_16x16x32_bf16 v[76:79], v[144:147], v[196:199], v[76:79]
	v_mfma_f32_16x16x32_bf16 v[72:75], v[160:163], v[196:199], v[72:75]
	v_mfma_f32_16x16x32_bf16 v[124:127], v[148:151], v[176:179], v[124:127]
	v_mfma_f32_16x16x32_bf16 v[120:123], v[164:167], v[176:179], v[120:123]
	v_mfma_f32_16x16x32_bf16 v[108:111], v[148:151], v[184:187], v[108:111]
	v_mfma_f32_16x16x32_bf16 v[104:107], v[164:167], v[184:187], v[104:107]
	v_mfma_f32_16x16x32_bf16 v[92:95], v[148:151], v[192:195], v[92:95]
	v_mfma_f32_16x16x32_bf16 v[88:91], v[164:167], v[192:195], v[88:91]
	v_mfma_f32_16x16x32_bf16 v[76:79], v[148:151], v[200:203], v[76:79]
	v_mfma_f32_16x16x32_bf16 v[72:75], v[164:167], v[200:203], v[72:75]
	s_setprio 0
	s_barrier
	s_add_i32 s34, 0, 0x1c000
	s_add_i32 s35, s61, s38
	v_add_u32_e32 v159, s34, v153
	v_lshl_add_u64 v[168:169], v[168:169], 0, s[10:11]
	s_mov_b32 m0, s35
	ds_read_b128 v[204:207], v159
	ds_read_b128 v[208:211], v159 offset:1024
	ds_read_b128 v[212:215], v159 offset:2048
	ds_read_b128 v[216:219], v159 offset:3072
	global_load_lds_dwordx4 v[168:169], off
	v_lshl_add_u64 v[168:169], v[220:221], 0, s[10:11]
	s_add_i32 m0, s35, 0x2000
	s_nop 0
	global_load_lds_dwordx4 v[168:169], off
	s_barrier
	s_waitcnt lgkmcnt(0)
	s_setprio 1
	s_waitcnt lgkmcnt(0)
	v_mfma_f32_16x16x32_bf16 v[116:119], v[204:207], v[172:175], v[116:119]
	v_mfma_f32_16x16x32_bf16 v[112:115], v[212:215], v[172:175], v[112:115]
	v_mfma_f32_16x16x32_bf16 v[100:103], v[204:207], v[180:183], v[100:103]
	v_mfma_f32_16x16x32_bf16 v[96:99], v[212:215], v[180:183], v[96:99]
	v_mfma_f32_16x16x32_bf16 v[84:87], v[204:207], v[188:191], v[84:87]
	v_mfma_f32_16x16x32_bf16 v[80:83], v[212:215], v[188:191], v[80:83]
	v_mfma_f32_16x16x32_bf16 v[68:71], v[204:207], v[196:199], v[68:71]
	v_mfma_f32_16x16x32_bf16 v[64:67], v[212:215], v[196:199], v[64:67]
	v_mfma_f32_16x16x32_bf16 v[116:119], v[208:211], v[176:179], v[116:119]
	v_mfma_f32_16x16x32_bf16 v[112:115], v[216:219], v[176:179], v[112:115]
	v_mfma_f32_16x16x32_bf16 v[100:103], v[208:211], v[184:187], v[100:103]
	v_mfma_f32_16x16x32_bf16 v[96:99], v[216:219], v[184:187], v[96:99]
	v_mfma_f32_16x16x32_bf16 v[84:87], v[208:211], v[192:195], v[84:87]
	v_mfma_f32_16x16x32_bf16 v[80:83], v[216:219], v[192:195], v[80:83]
	v_mfma_f32_16x16x32_bf16 v[68:71], v[208:211], v[200:203], v[68:71]
	v_mfma_f32_16x16x32_bf16 v[64:67], v[216:219], v[200:203], v[64:67]
	s_setprio 0
	s_mov_b32 m0, s45
	v_lshl_add_u64 v[168:169], v[222:223], 0, s[10:11]
	s_barrier
	ds_read_b128 v[172:175], v156 offset:49152
	ds_read_b128 v[176:179], v156 offset:50176
	ds_read_b128 v[180:183], v156 offset:51200
	ds_read_b128 v[184:187], v156 offset:52224
	ds_read_b128 v[188:191], v156 offset:53248
	ds_read_b128 v[192:195], v156 offset:54272
	ds_read_b128 v[196:199], v156 offset:55296
	ds_read_b128 v[200:203], v156 offset:56320
	global_load_lds_dwordx4 v[168:169], off
	v_lshl_add_u64 v[168:169], v[224:225], 0, s[10:11]
	s_mov_b32 m0, s46
	s_nop 0
	global_load_lds_dwordx4 v[168:169], off
	s_waitcnt vmcnt(10)
	s_barrier
	s_waitcnt lgkmcnt(0)
	s_setprio 1
	s_waitcnt lgkmcnt(0)
	v_mfma_f32_16x16x32_bf16 v[60:63], v[144:147], v[172:175], v[60:63]
	v_mfma_f32_16x16x32_bf16 v[56:59], v[160:163], v[172:175], v[56:59]
	v_mfma_f32_16x16x32_bf16 v[44:47], v[144:147], v[180:183], v[44:47]
	v_mfma_f32_16x16x32_bf16 v[40:43], v[160:163], v[180:183], v[40:43]
	v_mfma_f32_16x16x32_bf16 v[28:31], v[144:147], v[188:191], v[28:31]
	v_mfma_f32_16x16x32_bf16 v[24:27], v[160:163], v[188:191], v[24:27]
	v_mfma_f32_16x16x32_bf16 v[12:15], v[144:147], v[196:199], v[12:15]
	v_mfma_f32_16x16x32_bf16 v[8:11], v[160:163], v[196:199], v[8:11]
	v_mfma_f32_16x16x32_bf16 v[60:63], v[148:151], v[176:179], v[60:63]
	v_mfma_f32_16x16x32_bf16 v[56:59], v[164:167], v[176:179], v[56:59]
	v_mfma_f32_16x16x32_bf16 v[44:47], v[148:151], v[184:187], v[44:47]
	v_mfma_f32_16x16x32_bf16 v[40:43], v[164:167], v[184:187], v[40:43]
	v_mfma_f32_16x16x32_bf16 v[28:31], v[148:151], v[192:195], v[28:31]
	v_mfma_f32_16x16x32_bf16 v[24:27], v[164:167], v[192:195], v[24:27]
	v_mfma_f32_16x16x32_bf16 v[12:15], v[148:151], v[200:203], v[12:15]
	v_mfma_f32_16x16x32_bf16 v[8:11], v[164:167], v[200:203], v[8:11]
	s_setprio 0
	s_barrier
	s_add_u32 s30, s30, 0x80080
	s_addc_u32 s31, s31, 0
	s_add_i32 s34, s34, s38
	v_lshl_add_u64 v[252:253], s[30:31], 0, v[130:131]
	s_mov_b32 m0, s34
	s_nop 0
	global_load_lds_dwordx4 v[252:253], off
	v_lshl_add_u64 v[252:253], s[30:31], 0, v[134:135]
	s_add_i32 m0, s34, 0x2000
	s_nop 0
	global_load_lds_dwordx4 v[252:253], off
	ds_read_b128 v[144:147], v155
	ds_read_b128 v[148:151], v155 offset:1024
	ds_read_b128 v[160:163], v155 offset:2048
	ds_read_b128 v[164:167], v155 offset:3072
	s_waitcnt vmcnt(6)
	s_barrier
	s_setprio 1
	v_mfma_f32_16x16x32_bf16 v[52:55], v[204:207], v[172:175], v[52:55]
	v_mfma_f32_16x16x32_bf16 v[48:51], v[212:215], v[172:175], v[48:51]
	v_mfma_f32_16x16x32_bf16 v[36:39], v[204:207], v[180:183], v[36:39]
	v_mfma_f32_16x16x32_bf16 v[32:35], v[212:215], v[180:183], v[32:35]
	v_mfma_f32_16x16x32_bf16 v[20:23], v[204:207], v[188:191], v[20:23]
	v_mfma_f32_16x16x32_bf16 v[16:19], v[212:215], v[188:191], v[16:19]
	v_mfma_f32_16x16x32_bf16 v[4:7], v[204:207], v[196:199], v[4:7]
	v_mfma_f32_16x16x32_bf16 v[0:3], v[212:215], v[196:199], v[0:3]
	v_mfma_f32_16x16x32_bf16 v[52:55], v[208:211], v[176:179], v[52:55]
	v_mfma_f32_16x16x32_bf16 v[48:51], v[216:219], v[176:179], v[48:51]
	v_mfma_f32_16x16x32_bf16 v[36:39], v[208:211], v[184:187], v[36:39]
	v_mfma_f32_16x16x32_bf16 v[32:35], v[216:219], v[184:187], v[32:35]
	v_mfma_f32_16x16x32_bf16 v[20:23], v[208:211], v[192:195], v[20:23]
	v_mfma_f32_16x16x32_bf16 v[16:19], v[216:219], v[192:195], v[16:19]
	v_mfma_f32_16x16x32_bf16 v[4:7], v[208:211], v[200:203], v[4:7]
	v_mfma_f32_16x16x32_bf16 v[0:3], v[216:219], v[200:203], v[0:3]
	s_setprio 0
	s_add_i32 s60, s60, 2
	s_add_u32 s0, s0, 0x100
	s_addc_u32 s1, s1, 0
	s_add_u32 s58, s58, 0x100
	s_addc_u32 s59, s59, 0
	s_cmp_gt_u32 s60, 29
	s_barrier
	s_cbranch_scc0 .LBB0_1271
	v_lshl_add_u32 v148, s28, 8, v152
	v_ashrrev_i32_e32 v149, 31, v148
	v_lshl_add_u64 v[146:147], v[148:149], 2, s[8:9]
	v_lshl_or_b32 v144, s55, 8, v154
	v_ashrrev_i32_e32 v145, 31, v144
	v_lshlrev_b64 v[150:151], 1, v[144:145]
	v_lshlrev_b64 v[162:163], 14, v[148:149]
	v_or_b32_e32 v160, 16, v148
	v_ashrrev_i32_e32 v161, 31, v160
	s_mov_b32 s55, s20
	s_mov_b32 s28, s22
	s_mov_b64 s[30:31], s[26:27]
	s_mov_b64 s[34:35], s[24:25]
	v_fmamk_f32 v144, v236, 0x3a000000, v158
	v_mul_f32_e32 v145, 0x4b800000, v144
	v_cmp_gt_f32_e32 vcc, s50, v144
	s_nop 1
	v_cndmask_b32_e32 v144, v144, v145, vcc
	v_rsq_f32_e32 v149, v144
	v_lshl_add_u64 v[144:145], s[68:69], 0, v[162:163]
	v_lshl_add_u64 v[144:145], v[144:145], 0, v[150:151]
	v_lshl_add_u64 v[162:163], v[160:161], 2, s[8:9]
	v_mul_f32_e32 v159, 0x45800000, v149
	v_cndmask_b32_e32 v164, v149, v159, vcc
	v_pk_mul_f32 v[126:127], v[126:127], v[164:165] op_sel_hi:[1,0]
	v_pk_mul_f32 v[124:125], v[124:125], v[164:165] op_sel_hi:[1,0]
	v_pk_mul_f32 v[122:123], v[122:123], v[164:165] op_sel_hi:[1,0]
	v_pk_mul_f32 v[120:121], v[120:121], v[164:165] op_sel_hi:[1,0]
	v_pk_mul_f32 v[118:119], v[118:119], v[164:165] op_sel_hi:[1,0]
	v_pk_mul_f32 v[116:117], v[116:117], v[164:165] op_sel_hi:[1,0]
	v_pk_mul_f32 v[114:115], v[114:115], v[164:165] op_sel_hi:[1,0]
	v_pk_mul_f32 v[112:113], v[112:113], v[164:165] op_sel_hi:[1,0]
	v_max_f32_e32 v124, 0, v124
	v_max_f32_e32 v120, 0, v120
	v_max_f32_e32 v125, 0, v125
	v_max_f32_e32 v121, 0, v121
	v_max_f32_e32 v126, 0, v126
	v_max_f32_e32 v122, 0, v122
	v_max_f32_e32 v127, 0, v127
	v_max_f32_e32 v123, 0, v123
	v_max_f32_e32 v116, 0, v116
	v_max_f32_e32 v112, 0, v112
	v_max_f32_e32 v117, 0, v117
	v_max_f32_e32 v113, 0, v113
	v_max_f32_e32 v118, 0, v118
	v_max_f32_e32 v114, 0, v114
	v_max_f32_e32 v119, 0, v119
	v_max_f32_e32 v115, 0, v115
	v_mul_f32_e32 v124, v124, v124
	v_mul_f32_e32 v120, v120, v120
	v_mul_f32_e32 v125, v125, v125
	v_mul_f32_e32 v121, v121, v121
	v_mul_f32_e32 v126, v126, v126
	v_mul_f32_e32 v122, v122, v122
	v_mul_f32_e32 v127, v127, v127
	v_mul_f32_e32 v123, v123, v123
	v_mul_f32_e32 v116, v116, v116
	v_mul_f32_e32 v149, v112, v112
	v_mul_f32_e32 v117, v117, v117
	v_mul_f32_e32 v159, v113, v113
	v_mul_f32_e32 v118, v118, v118
	v_mul_f32_e32 v164, v114, v114
	v_mul_f32_e32 v119, v119, v119
	v_mul_f32_e32 v165, v115, v115
	v_cvt_pk_bf16_f32 v112, v124, v125
	v_cvt_pk_bf16_f32 v113, v126, v127
	v_cvt_pk_bf16_f32 v114, v120, v121
	v_cvt_pk_bf16_f32 v115, v122, v123
	v_cvt_pk_bf16_f32 v116, v116, v117
	v_cvt_pk_bf16_f32 v117, v118, v119
	v_cvt_pk_bf16_f32 v118, v149, v159
	v_cvt_pk_bf16_f32 v119, v164, v165
	global_store_dwordx4 v[144:145], v[112:115], off
	global_store_dwordx4 v[144:145], v[116:119], off offset:256
	v_lshlrev_b64 v[114:115], 14, v[160:161]
	v_or_b32_e32 v112, 32, v148
	v_lshl_add_u64 v[114:115], s[68:69], 0, v[114:115]
	v_ashrrev_i32_e32 v113, 31, v112
	v_lshl_add_u64 v[114:115], v[114:115], 0, v[150:151]
	v_fmamk_f32 v116, v237, 0x3a000000, v158
	v_mul_f32_e32 v117, 0x4b800000, v116
	v_cmp_gt_f32_e32 vcc, s50, v116
	s_nop 1
	v_cndmask_b32_e32 v116, v116, v117, vcc
	v_rsq_f32_e32 v118, v116
	v_lshl_add_u64 v[116:117], v[112:113], 2, s[8:9]
	v_mul_f32_e32 v119, 0x45800000, v118
	v_cndmask_b32_e32 v118, v118, v119, vcc
	v_pk_mul_f32 v[110:111], v[110:111], v[118:119] op_sel_hi:[1,0]
	v_pk_mul_f32 v[108:109], v[108:109], v[118:119] op_sel_hi:[1,0]
	v_pk_mul_f32 v[106:107], v[106:107], v[118:119] op_sel_hi:[1,0]
	v_pk_mul_f32 v[104:105], v[104:105], v[118:119] op_sel_hi:[1,0]
	v_pk_mul_f32 v[102:103], v[102:103], v[118:119] op_sel_hi:[1,0]
	v_pk_mul_f32 v[100:101], v[100:101], v[118:119] op_sel_hi:[1,0]
	v_pk_mul_f32 v[98:99], v[98:99], v[118:119] op_sel_hi:[1,0]
	v_pk_mul_f32 v[96:97], v[96:97], v[118:119] op_sel_hi:[1,0]
	v_max_f32_e32 v108, 0, v108
	v_max_f32_e32 v104, 0, v104
	v_max_f32_e32 v109, 0, v109
	v_max_f32_e32 v105, 0, v105
	v_max_f32_e32 v110, 0, v110
	v_max_f32_e32 v106, 0, v106
	v_max_f32_e32 v111, 0, v111
	v_max_f32_e32 v107, 0, v107
	v_max_f32_e32 v100, 0, v100
	v_max_f32_e32 v96, 0, v96
	v_max_f32_e32 v101, 0, v101
	v_max_f32_e32 v97, 0, v97
	v_max_f32_e32 v102, 0, v102
	v_max_f32_e32 v98, 0, v98
	v_max_f32_e32 v103, 0, v103
	v_max_f32_e32 v99, 0, v99
	v_mul_f32_e32 v108, v108, v108
	v_mul_f32_e32 v104, v104, v104
	v_mul_f32_e32 v109, v109, v109
	v_mul_f32_e32 v105, v105, v105
	v_mul_f32_e32 v110, v110, v110
	v_mul_f32_e32 v106, v106, v106
	v_mul_f32_e32 v111, v111, v111
	v_mul_f32_e32 v107, v107, v107
	v_mul_f32_e32 v100, v100, v100
	v_mul_f32_e32 v118, v96, v96
	v_mul_f32_e32 v101, v101, v101
	v_mul_f32_e32 v119, v97, v97
	v_mul_f32_e32 v102, v102, v102
	v_mul_f32_e32 v120, v98, v98
	v_mul_f32_e32 v103, v103, v103
	v_mul_f32_e32 v121, v99, v99
	v_cvt_pk_bf16_f32 v96, v108, v109
	v_cvt_pk_bf16_f32 v97, v110, v111
	v_cvt_pk_bf16_f32 v98, v104, v105
	v_cvt_pk_bf16_f32 v99, v106, v107
	v_cvt_pk_bf16_f32 v100, v100, v101
	v_cvt_pk_bf16_f32 v101, v102, v103
	v_cvt_pk_bf16_f32 v102, v118, v119
	v_cvt_pk_bf16_f32 v103, v120, v121
	global_store_dwordx4 v[114:115], v[96:99], off
	global_store_dwordx4 v[114:115], v[100:103], off offset:256
	v_lshlrev_b64 v[98:99], 14, v[112:113]
	v_or_b32_e32 v96, 48, v148
	v_lshl_add_u64 v[98:99], s[68:69], 0, v[98:99]
	v_ashrrev_i32_e32 v97, 31, v96
	v_lshl_add_u64 v[98:99], v[98:99], 0, v[150:151]
	v_fmamk_f32 v100, v238, 0x3a000000, v158
	v_mul_f32_e32 v101, 0x4b800000, v100
	v_cmp_gt_f32_e32 vcc, s50, v100
	s_nop 1
	v_cndmask_b32_e32 v100, v100, v101, vcc
	v_rsq_f32_e32 v102, v100
	v_lshl_add_u64 v[100:101], v[96:97], 2, s[8:9]
	v_mul_f32_e32 v103, 0x45800000, v102
	v_cndmask_b32_e32 v102, v102, v103, vcc
	v_pk_mul_f32 v[94:95], v[94:95], v[102:103] op_sel_hi:[1,0]
	v_pk_mul_f32 v[92:93], v[92:93], v[102:103] op_sel_hi:[1,0]
	v_pk_mul_f32 v[90:91], v[90:91], v[102:103] op_sel_hi:[1,0]
	v_pk_mul_f32 v[88:89], v[88:89], v[102:103] op_sel_hi:[1,0]
	v_pk_mul_f32 v[86:87], v[86:87], v[102:103] op_sel_hi:[1,0]
	v_pk_mul_f32 v[84:85], v[84:85], v[102:103] op_sel_hi:[1,0]
	v_pk_mul_f32 v[82:83], v[82:83], v[102:103] op_sel_hi:[1,0]
	v_pk_mul_f32 v[80:81], v[80:81], v[102:103] op_sel_hi:[1,0]
	v_max_f32_e32 v92, 0, v92
	v_max_f32_e32 v88, 0, v88
	v_max_f32_e32 v93, 0, v93
	v_max_f32_e32 v89, 0, v89
	v_max_f32_e32 v94, 0, v94
	v_max_f32_e32 v90, 0, v90
	v_max_f32_e32 v95, 0, v95
	v_max_f32_e32 v91, 0, v91
	v_max_f32_e32 v84, 0, v84
	v_max_f32_e32 v80, 0, v80
	v_max_f32_e32 v85, 0, v85
	v_max_f32_e32 v81, 0, v81
	v_max_f32_e32 v86, 0, v86
	v_max_f32_e32 v82, 0, v82
	v_max_f32_e32 v87, 0, v87
	v_max_f32_e32 v83, 0, v83
	v_mul_f32_e32 v92, v92, v92
	v_mul_f32_e32 v88, v88, v88
	v_mul_f32_e32 v93, v93, v93
	v_mul_f32_e32 v89, v89, v89
	v_mul_f32_e32 v94, v94, v94
	v_mul_f32_e32 v90, v90, v90
	v_mul_f32_e32 v95, v95, v95
	v_mul_f32_e32 v91, v91, v91
	v_mul_f32_e32 v84, v84, v84
	v_mul_f32_e32 v102, v80, v80
	v_mul_f32_e32 v85, v85, v85
	v_mul_f32_e32 v103, v81, v81
	v_mul_f32_e32 v86, v86, v86
	v_mul_f32_e32 v104, v82, v82
	v_mul_f32_e32 v87, v87, v87
	v_mul_f32_e32 v105, v83, v83
	v_cvt_pk_bf16_f32 v80, v92, v93
	v_cvt_pk_bf16_f32 v81, v94, v95
	v_cvt_pk_bf16_f32 v82, v88, v89
	v_cvt_pk_bf16_f32 v83, v90, v91
	v_cvt_pk_bf16_f32 v84, v84, v85
	v_cvt_pk_bf16_f32 v85, v86, v87
	v_cvt_pk_bf16_f32 v86, v102, v103
	v_cvt_pk_bf16_f32 v87, v104, v105
	global_store_dwordx4 v[98:99], v[80:83], off
	global_store_dwordx4 v[98:99], v[84:87], off offset:256
	v_fmamk_f32 v80, v239, 0x3a000000, v158
	v_mul_f32_e32 v81, 0x4b800000, v80
	v_cmp_gt_f32_e32 vcc, s50, v80
	s_nop 1
	v_cndmask_b32_e32 v80, v80, v81, vcc
	v_rsq_f32_e32 v82, v80
	v_lshlrev_b64 v[80:81], 14, v[96:97]
	v_lshl_add_u64 v[80:81], s[68:69], 0, v[80:81]
	v_lshl_add_u64 v[80:81], v[80:81], 0, v[150:151]
	v_mul_f32_e32 v83, 0x45800000, v82
	v_cndmask_b32_e32 v82, v82, v83, vcc
	v_pk_mul_f32 v[78:79], v[78:79], v[82:83] op_sel_hi:[1,0]
	v_pk_mul_f32 v[76:77], v[76:77], v[82:83] op_sel_hi:[1,0]
	v_pk_mul_f32 v[74:75], v[74:75], v[82:83] op_sel_hi:[1,0]
	v_pk_mul_f32 v[72:73], v[72:73], v[82:83] op_sel_hi:[1,0]
	v_pk_mul_f32 v[70:71], v[70:71], v[82:83] op_sel_hi:[1,0]
	v_pk_mul_f32 v[68:69], v[68:69], v[82:83] op_sel_hi:[1,0]
	v_pk_mul_f32 v[66:67], v[66:67], v[82:83] op_sel_hi:[1,0]
	v_pk_mul_f32 v[64:65], v[64:65], v[82:83] op_sel_hi:[1,0]
	v_max_f32_e32 v76, 0, v76
	v_max_f32_e32 v72, 0, v72
	v_max_f32_e32 v77, 0, v77
	v_max_f32_e32 v73, 0, v73
	v_max_f32_e32 v78, 0, v78
	v_max_f32_e32 v74, 0, v74
	v_max_f32_e32 v79, 0, v79
	v_max_f32_e32 v75, 0, v75
	v_max_f32_e32 v68, 0, v68
	v_max_f32_e32 v64, 0, v64
	v_max_f32_e32 v69, 0, v69
	v_max_f32_e32 v65, 0, v65
	v_max_f32_e32 v70, 0, v70
	v_max_f32_e32 v66, 0, v66
	v_max_f32_e32 v71, 0, v71
	v_max_f32_e32 v67, 0, v67
	v_mul_f32_e32 v76, v76, v76
	v_mul_f32_e32 v72, v72, v72
	v_mul_f32_e32 v77, v77, v77
	v_mul_f32_e32 v73, v73, v73
	v_mul_f32_e32 v78, v78, v78
	v_mul_f32_e32 v74, v74, v74
	v_mul_f32_e32 v79, v79, v79
	v_mul_f32_e32 v75, v75, v75
	v_mul_f32_e32 v68, v68, v68
	v_mul_f32_e32 v82, v64, v64
	v_mul_f32_e32 v69, v69, v69
	v_mul_f32_e32 v83, v65, v65
	v_mul_f32_e32 v70, v70, v70
	v_mul_f32_e32 v84, v66, v66
	v_mul_f32_e32 v71, v71, v71
	v_mul_f32_e32 v85, v67, v67
	v_cvt_pk_bf16_f32 v64, v76, v77
	v_cvt_pk_bf16_f32 v65, v78, v79
	v_cvt_pk_bf16_f32 v66, v72, v73
	v_cvt_pk_bf16_f32 v67, v74, v75
	v_cvt_pk_bf16_f32 v68, v68, v69
	v_cvt_pk_bf16_f32 v69, v70, v71
	v_cvt_pk_bf16_f32 v70, v82, v83
	v_cvt_pk_bf16_f32 v71, v84, v85
	global_store_dwordx4 v[80:81], v[64:67], off
	global_store_dwordx4 v[80:81], v[68:71], off offset:256
	v_lshl_add_u64 v[64:65], v[144:145], 0, s[12:13]
	v_fmamk_f32 v66, v240, 0x3a000000, v158
	v_mul_f32_e32 v67, 0x4b800000, v66
	v_cmp_gt_f32_e32 vcc, s50, v66
	s_nop 1
	v_cndmask_b32_e32 v66, v66, v67, vcc
	v_rsq_f32_e32 v68, v66
	v_add_co_u32_e64 v66, s[0:1], s51, v144
	v_mul_f32_e32 v69, 0x45800000, v68
	v_cndmask_b32_e32 v68, v68, v69, vcc
	v_pk_mul_f32 v[62:63], v[62:63], v[68:69] op_sel_hi:[1,0]
	v_pk_mul_f32 v[60:61], v[60:61], v[68:69] op_sel_hi:[1,0]
	v_pk_mul_f32 v[58:59], v[58:59], v[68:69] op_sel_hi:[1,0]
	v_pk_mul_f32 v[56:57], v[56:57], v[68:69] op_sel_hi:[1,0]
	v_pk_mul_f32 v[54:55], v[54:55], v[68:69] op_sel_hi:[1,0]
	v_pk_mul_f32 v[52:53], v[52:53], v[68:69] op_sel_hi:[1,0]
	v_pk_mul_f32 v[50:51], v[50:51], v[68:69] op_sel_hi:[1,0]
	v_pk_mul_f32 v[48:49], v[48:49], v[68:69] op_sel_hi:[1,0]
	v_max_f32_e32 v60, 0, v60
	v_max_f32_e32 v56, 0, v56
	v_max_f32_e32 v61, 0, v61
	v_max_f32_e32 v57, 0, v57
	v_max_f32_e32 v62, 0, v62
	v_max_f32_e32 v58, 0, v58
	v_max_f32_e32 v63, 0, v63
	v_max_f32_e32 v59, 0, v59
	v_max_f32_e32 v52, 0, v52
	v_max_f32_e32 v48, 0, v48
	v_max_f32_e32 v53, 0, v53
	v_max_f32_e32 v49, 0, v49
	v_max_f32_e32 v54, 0, v54
	v_max_f32_e32 v50, 0, v50
	v_max_f32_e32 v55, 0, v55
	v_max_f32_e32 v51, 0, v51
	v_mul_f32_e32 v60, v60, v60
	v_mul_f32_e32 v56, v56, v56
	v_mul_f32_e32 v61, v61, v61
	v_mul_f32_e32 v57, v57, v57
	v_mul_f32_e32 v62, v62, v62
	v_mul_f32_e32 v58, v58, v58
	v_mul_f32_e32 v63, v63, v63
	v_mul_f32_e32 v59, v59, v59
	v_addc_co_u32_e64 v67, s[0:1], 0, v145, s[0:1]
	v_mul_f32_e32 v52, v52, v52
	v_mul_f32_e32 v68, v48, v48
	v_mul_f32_e32 v53, v53, v53
	v_mul_f32_e32 v69, v49, v49
	v_mul_f32_e32 v54, v54, v54
	v_mul_f32_e32 v70, v50, v50
	v_mul_f32_e32 v55, v55, v55
	v_mul_f32_e32 v71, v51, v51
	v_cvt_pk_bf16_f32 v48, v60, v61
	v_cvt_pk_bf16_f32 v49, v62, v63
	v_cvt_pk_bf16_f32 v50, v56, v57
	v_cvt_pk_bf16_f32 v51, v58, v59
	v_cvt_pk_bf16_f32 v52, v52, v53
	v_cvt_pk_bf16_f32 v53, v54, v55
	v_cvt_pk_bf16_f32 v54, v68, v69
	v_cvt_pk_bf16_f32 v55, v70, v71
	global_store_dwordx4 v[66:67], v[48:51], off
	global_store_dwordx4 v[64:65], v[52:55], off offset:256
	v_lshl_add_u64 v[48:49], v[144:145], 0, s[14:15]
	v_fmamk_f32 v50, v241, 0x3a000000, v158
	v_mul_f32_e32 v51, 0x4b800000, v50
	v_cmp_gt_f32_e32 vcc, s50, v50
	s_nop 1
	v_cndmask_b32_e32 v50, v50, v51, vcc
	v_rsq_f32_e32 v52, v50
	v_add_co_u32_e64 v50, s[0:1], s52, v144
	v_mul_f32_e32 v53, 0x45800000, v52
	v_cndmask_b32_e32 v52, v52, v53, vcc
	v_pk_mul_f32 v[46:47], v[46:47], v[52:53] op_sel_hi:[1,0]
	v_pk_mul_f32 v[44:45], v[44:45], v[52:53] op_sel_hi:[1,0]
	v_pk_mul_f32 v[42:43], v[42:43], v[52:53] op_sel_hi:[1,0]
	v_pk_mul_f32 v[40:41], v[40:41], v[52:53] op_sel_hi:[1,0]
	v_pk_mul_f32 v[38:39], v[38:39], v[52:53] op_sel_hi:[1,0]
	v_pk_mul_f32 v[36:37], v[36:37], v[52:53] op_sel_hi:[1,0]
	v_pk_mul_f32 v[34:35], v[34:35], v[52:53] op_sel_hi:[1,0]
	v_pk_mul_f32 v[32:33], v[32:33], v[52:53] op_sel_hi:[1,0]
	v_max_f32_e32 v44, 0, v44
	v_max_f32_e32 v40, 0, v40
	v_max_f32_e32 v45, 0, v45
	v_max_f32_e32 v41, 0, v41
	v_max_f32_e32 v46, 0, v46
	v_max_f32_e32 v42, 0, v42
	v_max_f32_e32 v47, 0, v47
	v_max_f32_e32 v43, 0, v43
	v_max_f32_e32 v36, 0, v36
	v_max_f32_e32 v32, 0, v32
	v_max_f32_e32 v37, 0, v37
	v_max_f32_e32 v33, 0, v33
	v_max_f32_e32 v38, 0, v38
	v_max_f32_e32 v34, 0, v34
	v_max_f32_e32 v39, 0, v39
	v_max_f32_e32 v35, 0, v35
	v_mul_f32_e32 v44, v44, v44
	v_mul_f32_e32 v40, v40, v40
	v_mul_f32_e32 v45, v45, v45
	v_mul_f32_e32 v41, v41, v41
	v_mul_f32_e32 v46, v46, v46
	v_mul_f32_e32 v42, v42, v42
	v_mul_f32_e32 v47, v47, v47
	v_mul_f32_e32 v43, v43, v43
	v_addc_co_u32_e64 v51, s[0:1], 0, v145, s[0:1]
	v_mul_f32_e32 v36, v36, v36
	v_mul_f32_e32 v52, v32, v32
	v_mul_f32_e32 v37, v37, v37
	v_mul_f32_e32 v53, v33, v33
	v_mul_f32_e32 v38, v38, v38
	v_mul_f32_e32 v54, v34, v34
	v_mul_f32_e32 v39, v39, v39
	v_mul_f32_e32 v55, v35, v35
	v_cvt_pk_bf16_f32 v32, v44, v45
	v_cvt_pk_bf16_f32 v33, v46, v47
	v_cvt_pk_bf16_f32 v34, v40, v41
	v_cvt_pk_bf16_f32 v35, v42, v43
	v_cvt_pk_bf16_f32 v36, v36, v37
	v_cvt_pk_bf16_f32 v37, v38, v39
	v_cvt_pk_bf16_f32 v38, v52, v53
	v_cvt_pk_bf16_f32 v39, v54, v55
	global_store_dwordx4 v[50:51], v[32:35], off
	global_store_dwordx4 v[48:49], v[36:39], off offset:256
	v_lshl_add_u64 v[32:33], v[144:145], 0, s[16:17]
	v_fmamk_f32 v34, v242, 0x3a000000, v158
	v_mul_f32_e32 v35, 0x4b800000, v34
	v_cmp_gt_f32_e32 vcc, s50, v34
	s_nop 1
	v_cndmask_b32_e32 v34, v34, v35, vcc
	v_rsq_f32_e32 v36, v34
	v_add_co_u32_e64 v34, s[0:1], s53, v144
	v_mul_f32_e32 v37, 0x45800000, v36
	v_cndmask_b32_e32 v36, v36, v37, vcc
	v_pk_mul_f32 v[30:31], v[30:31], v[36:37] op_sel_hi:[1,0]
	v_pk_mul_f32 v[28:29], v[28:29], v[36:37] op_sel_hi:[1,0]
	v_pk_mul_f32 v[26:27], v[26:27], v[36:37] op_sel_hi:[1,0]
	v_pk_mul_f32 v[24:25], v[24:25], v[36:37] op_sel_hi:[1,0]
	v_pk_mul_f32 v[22:23], v[22:23], v[36:37] op_sel_hi:[1,0]
	v_pk_mul_f32 v[20:21], v[20:21], v[36:37] op_sel_hi:[1,0]
	v_pk_mul_f32 v[18:19], v[18:19], v[36:37] op_sel_hi:[1,0]
	v_pk_mul_f32 v[16:17], v[16:17], v[36:37] op_sel_hi:[1,0]
	v_max_f32_e32 v28, 0, v28
	v_max_f32_e32 v24, 0, v24
	v_max_f32_e32 v29, 0, v29
	v_max_f32_e32 v25, 0, v25
	v_max_f32_e32 v30, 0, v30
	v_max_f32_e32 v26, 0, v26
	v_max_f32_e32 v31, 0, v31
	v_max_f32_e32 v27, 0, v27
	v_max_f32_e32 v20, 0, v20
	v_max_f32_e32 v16, 0, v16
	v_max_f32_e32 v21, 0, v21
	v_max_f32_e32 v17, 0, v17
	v_max_f32_e32 v22, 0, v22
	v_max_f32_e32 v18, 0, v18
	v_max_f32_e32 v23, 0, v23
	v_max_f32_e32 v19, 0, v19
	v_mul_f32_e32 v28, v28, v28
	v_mul_f32_e32 v24, v24, v24
	v_mul_f32_e32 v29, v29, v29
	v_mul_f32_e32 v25, v25, v25
	v_mul_f32_e32 v30, v30, v30
	v_mul_f32_e32 v26, v26, v26
	v_mul_f32_e32 v31, v31, v31
	v_mul_f32_e32 v27, v27, v27
	v_addc_co_u32_e64 v35, s[0:1], 0, v145, s[0:1]
	v_mul_f32_e32 v20, v20, v20
	v_mul_f32_e32 v36, v16, v16
	v_mul_f32_e32 v21, v21, v21
	v_mul_f32_e32 v37, v17, v17
	v_mul_f32_e32 v22, v22, v22
	v_mul_f32_e32 v38, v18, v18
	v_mul_f32_e32 v23, v23, v23
	v_mul_f32_e32 v39, v19, v19
	v_cvt_pk_bf16_f32 v16, v28, v29
	v_cvt_pk_bf16_f32 v17, v30, v31
	v_cvt_pk_bf16_f32 v18, v24, v25
	v_cvt_pk_bf16_f32 v19, v26, v27
	v_cvt_pk_bf16_f32 v20, v20, v21
	v_cvt_pk_bf16_f32 v21, v22, v23
	v_cvt_pk_bf16_f32 v22, v36, v37
	v_cvt_pk_bf16_f32 v23, v38, v39
	global_store_dwordx4 v[34:35], v[16:19], off
	global_store_dwordx4 v[32:33], v[20:23], off offset:256
	s_and_b64 vcc, exec, s[2:3]
	v_lshl_add_u64 v[16:17], v[144:145], 0, s[18:19]
	v_fmamk_f32 v18, v243, 0x3a000000, v158
	v_mul_f32_e32 v19, 0x4b800000, v18
	v_cmp_gt_f32_e64 s[0:1], s50, v18
	s_nop 1
	v_cndmask_b32_e64 v18, v18, v19, s[0:1]
	v_rsq_f32_e32 v20, v18
	v_add_co_u32_e64 v18, s[2:3], s54, v144
	v_mul_f32_e32 v21, 0x45800000, v20
	v_cndmask_b32_e64 v20, v20, v21, s[0:1]
	v_pk_mul_f32 v[14:15], v[14:15], v[20:21] op_sel_hi:[1,0]
	v_pk_mul_f32 v[12:13], v[12:13], v[20:21] op_sel_hi:[1,0]
	v_pk_mul_f32 v[10:11], v[10:11], v[20:21] op_sel_hi:[1,0]
	v_pk_mul_f32 v[8:9], v[8:9], v[20:21] op_sel_hi:[1,0]
	v_pk_mul_f32 v[6:7], v[6:7], v[20:21] op_sel_hi:[1,0]
	v_pk_mul_f32 v[4:5], v[4:5], v[20:21] op_sel_hi:[1,0]
	v_pk_mul_f32 v[2:3], v[2:3], v[20:21] op_sel_hi:[1,0]
	v_pk_mul_f32 v[0:1], v[0:1], v[20:21] op_sel_hi:[1,0]
	v_max_f32_e32 v12, 0, v12
	v_max_f32_e32 v8, 0, v8
	v_max_f32_e32 v13, 0, v13
	v_max_f32_e32 v9, 0, v9
	v_max_f32_e32 v14, 0, v14
	v_max_f32_e32 v10, 0, v10
	v_max_f32_e32 v15, 0, v15
	v_max_f32_e32 v11, 0, v11
	v_max_f32_e32 v4, 0, v4
	v_max_f32_e32 v0, 0, v0
	v_max_f32_e32 v5, 0, v5
	v_max_f32_e32 v1, 0, v1
	v_max_f32_e32 v6, 0, v6
	v_max_f32_e32 v2, 0, v2
	v_max_f32_e32 v7, 0, v7
	v_max_f32_e32 v3, 0, v3
	v_mul_f32_e32 v12, v12, v12
	v_mul_f32_e32 v8, v8, v8
	v_mul_f32_e32 v13, v13, v13
	v_mul_f32_e32 v9, v9, v9
	v_mul_f32_e32 v14, v14, v14
	v_mul_f32_e32 v10, v10, v10
	v_mul_f32_e32 v15, v15, v15
	v_mul_f32_e32 v11, v11, v11
	v_addc_co_u32_e64 v19, s[2:3], 0, v145, s[2:3]
	v_mul_f32_e32 v4, v4, v4
	v_mul_f32_e32 v20, v0, v0
	v_mul_f32_e32 v5, v5, v5
	v_mul_f32_e32 v21, v1, v1
	v_mul_f32_e32 v6, v6, v6
	v_mul_f32_e32 v22, v2, v2
	v_mul_f32_e32 v7, v7, v7
	v_mul_f32_e32 v23, v3, v3
	v_cvt_pk_bf16_f32 v0, v12, v13
	v_cvt_pk_bf16_f32 v1, v14, v15
	v_cvt_pk_bf16_f32 v2, v8, v9
	v_cvt_pk_bf16_f32 v3, v10, v11
	v_cvt_pk_bf16_f32 v4, v4, v5
	v_cvt_pk_bf16_f32 v5, v6, v7
	v_cvt_pk_bf16_f32 v6, v20, v21
	v_cvt_pk_bf16_f32 v7, v22, v23
	global_store_dwordx4 v[18:19], v[0:3], off
	global_store_dwordx4 v[16:17], v[4:7], off offset:256
	s_cbranch_vccz .LBB0_1264
	s_waitcnt vmcnt(0)
	s_cmpk_gt_u32 s33, 0xff
	s_cbranch_scc1 .LBB0_1275
	s_barrier
